# throttle + scan copy removal + score immediates + exact scan vmcnt waits
# baseline (speedup 1.0000x reference)
; __device__ __forceinline__ uint2 pack4v(f32x4 a) { uint2 r; r.x = pack2(a[0], a[1]); r.y = pack2(a[2], a[3]); return r; }
; __device__ __forceinline__ f32x4 mfma16(bf16x8 a, bf16x8 b, f32x4 c) { return __builtin_amdgcn_mfma_f32_16x16x32_bf16(a, b, c, 0, 0, 0); }
; __device__ __forceinline__ void scan_step(const ScanCtx& c, int n, const u16* Sc, u16* Sn, f32x4 (&S)[4], bf16x8 (&W_)[2], ...
;   const int w = c.w, lane = c.lane;
;   const size_t cb = (size_t)(c.seq * 128 + n) * 4096;
;   bf16x8 Sf[2][4];
; #pragma unroll
;   for (int kb = 0; kb < 2; ++kb)
; #pragma unroll
;     for (int nt = 0; nt < 4; ++nt) Sf[kb][nt] = *(const bf16x8*)(Sc + ((kb * 4 + nt) * 64 + lane) * 8);
; #pragma unroll
;   for (int nt = 0; nt < 4; ++nt) {
;     f32x4 a = {0.f, 0.f, 0.f, 0.f};
;     a = mfma16(W_[0], Sf[0][nt], a); a = mfma16(W_[1], Sf[1][nt], a);
;     f32x4 vn = U_[nt] - a;
;     *(uint2*)(c.Vbuf + (((w >> 1) * 4 + nt) * 64 + lane) * 8 + (w & 1) * 4) = pack4v(vn);
;   }
;   __syncthreads();
.LBB0_483:
	ds_read_b128 v[130:133], v126
	ds_read_b128 v[134:137], v126 offset:1024
	ds_read_b128 v[142:145], v126 offset:2048
	ds_read_b128 v[146:149], v126 offset:3072
	ds_read_b128 v[150:153], v126 offset:4096
	ds_read_b128 v[158:161], v126 offset:5120
	ds_read_b128 v[162:165], v126 offset:6144
	ds_read_b128 v[166:169], v126 offset:7168
	s_waitcnt vmcnt(27)


; __device__ __forceinline__ uint2 pack4v(f32x4 a) { uint2 r; r.x = pack2(a[0], a[1]); r.y = pack2(a[2], a[3]); return r; }
; __device__ __forceinline__ f32x4 mfma16(bf16x8 a, bf16x8 b, f32x4 c) { return __builtin_amdgcn_mfma_f32_16x16x32_bf16(a, b, c, 0, 0, 0); }
; __device__ __forceinline__ void scan_step(const ScanCtx& c, int n, const u16* Sc, u16* Sn, f32x4 (&S)[4], bf16x8 (&W_)[2], ...
;     ...
;   bf16x8 Sf[2][4];
; #pragma unroll
;   for (int kb = 0; kb < 2; ++kb)
; #pragma unroll
;     for (int nt = 0; nt < 4; ++nt) Sf[kb][nt] = *(const bf16x8*)(Sc + ((kb * 4 + nt) * 64 + lane) * 8);
; #pragma unroll
;   for (int nt = 0; nt < 4; ++nt) {
;     f32x4 a = {0.f, 0.f, 0.f, 0.f};
;     a = mfma16(W_[0], Sf[0][nt], a); a = mfma16(W_[1], Sf[1][nt], a);
;     f32x4 vn = U_[nt] - a;
;     *(uint2*)(c.Vbuf + (((w >> 1) * 4 + nt) * 64 + lane) * 8 + (w & 1) * 4) = pack4v(vn);
;   }
;   __syncthreads();
	v_mov_b32_e32 v118, v194
	v_pk_mul_f32 v[102:103], v[102:103], v[118:119] op_sel_hi:[1,0]
	s_waitcnt lgkmcnt(7)
	v_mfma_f32_16x16x32_bf16 v[138:141], v[170:173], v[130:133], 0
	v_mul_f32_e64 v100, v100, v118
	v_mul_f32_e64 v101, v101, v118
	s_add_i32 s13, s12, 2
	s_waitcnt lgkmcnt(3)
	v_mfma_f32_16x16x32_bf16 v[138:141], v[174:177], v[150:153], v[138:141]
	v_mfma_f32_16x16x32_bf16 v[154:157], v[170:173], v[134:137], 0
	s_nop 6
	v_sub_f32_e32 v79, v181, v141
	v_sub_f32_e32 v78, v180, v140
	v_sub_f32_e32 v77, v179, v139
	v_sub_f32_e32 v76, v178, v138
	v_cvt_pk_bf16_f32 v138, v76, v77
	v_cvt_pk_bf16_f32 v139, v78, v79
	s_waitcnt lgkmcnt(2)
	v_mfma_f32_16x16x32_bf16 v[76:79], v[174:177], v[158:161], v[154:157]
	s_nop 7
	v_sub_f32_e32 v79, v185, v79
	v_sub_f32_e32 v78, v184, v78
	v_sub_f32_e32 v77, v183, v77
	v_sub_f32_e32 v76, v182, v76
	v_mfma_f32_16x16x32_bf16 v[72:75], v[170:173], v[142:145], 0
	v_cvt_pk_bf16_f32 v76, v76, v77
	v_cvt_pk_bf16_f32 v77, v78, v79
	ds_write2st64_b64 v127, v[138:139], v[76:77] offset0:32 offset1:34
	v_mfma_f32_16x16x32_bf16 v[52:55], v[170:173], v[146:149], 0
	v_mul_f32_e64 v78, v110, v118
	v_mul_f32_e64 v79, v111, v118
	v_pk_mul_f32 v[76:77], v[108:109], v[118:119] op_sel_hi:[1,0]
	s_waitcnt lgkmcnt(2)
	v_mfma_f32_16x16x32_bf16 v[72:75], v[174:177], v[162:165], v[72:75]
	s_waitcnt lgkmcnt(1)
	v_mfma_f32_16x16x32_bf16 v[48:51], v[174:177], v[166:169], v[52:55]
	s_nop 5
	v_sub_f32_e32 v71, v189, v75
	v_sub_f32_e32 v70, v188, v74
	v_sub_f32_e32 v69, v187, v73
	v_sub_f32_e32 v68, v186, v72
	v_sub_f32_e32 v51, v193, v51
	v_sub_f32_e32 v50, v192, v50
	v_sub_f32_e32 v49, v191, v49
	v_sub_f32_e32 v48, v190, v48
	v_cvt_pk_bf16_f32 v68, v68, v69
	v_cvt_pk_bf16_f32 v69, v70, v71
	v_cvt_pk_bf16_f32 v48, v48, v49
	v_cvt_pk_bf16_f32 v49, v50, v51
	ds_write_b64 v128, v[68:69] offset:16384
	ds_write_b64 v129, v[48:49] offset:16384
	s_waitcnt vmcnt(17)
	v_mfma_f32_16x16x32_bf16 v[48:51], v[4:7], v[130:133], 0
	s_waitcnt lgkmcnt(0)
	s_barrier
; __device__ __forceinline__ void scan_load(const ScanCtx& c, int n, bf16x8 (&W_)[2], bf16x8 (&QH_)[2], bf16x8 (&QK_)[2],
;                                           bf16x8 (&KT_)[2], f32x4 (&U_)[4], float& g_) {
;   n = n < 128 ? n : 127;
;   const size_t cb = (size_t)(c.seq * 128 + n) * 4096;
; #pragma unroll
;   for (int kb = 0; kb < 2; ++kb) {
;     const size_t o = cb + ((c.w * 2 + kb) * 64 + c.lane) * 8;
;     W_[kb] = *(const bf16x8*)(c.DNW + o); QH_[kb] = *(const bf16x8*)(c.DNQH + o); QK_[kb] = *(const bf16x8*)(c.DNQK + o); KT_[kb] = *(const bf16x8*)(c.DNKT + o);
;   }
; #pragma unroll
;   for (int nt = 0; nt < 4; ++nt) U_[nt] = *(const f32x4*)(c.Ubuf + cb + ((c.w * 4 + nt) * 64 + c.lane) * 4);
;   g_ = c.glp[c.seq * 128 + n];
; }
; __device__ __forceinline__ void scan_step(const ScanCtx& c, int n, const u16* Sc, u16* Sn, f32x4 (&S)[4], bf16x8 (&W_)[2], ...
;   const int w = c.w, lane = c.lane;
;   const size_t cb = (size_t)(c.seq * 128 + n) * 4096;
;   bf16x8 Sf[2][4];
; #pragma unroll
;   for (int kb = 0; kb < 2; ++kb)
; #pragma unroll
;     for (int nt = 0; nt < 4; ++nt) Sf[kb][nt] = *(const bf16x8*)(Sc + ((kb * 4 + nt) * 64 + lane) * 8);
; #pragma unroll
;   for (int nt = 0; nt < 4; ++nt) {
;     f32x4 a = {0.f, 0.f, 0.f, 0.f};
;     a = mfma16(W_[0], Sf[0][nt], a); a = mfma16(W_[1], Sf[1][nt], a);
;     f32x4 vn = U_[nt] - a;
;     *(uint2*)(c.Vbuf + (((w >> 1) * 4 + nt) * 64 + lane) * 8 + (w & 1) * 4) = pack4v(vn);
;   }
;   __syncthreads();
;   bf16x8 Vf[2][4];
; #pragma unroll
;   for (int kb = 0; kb < 2; ++kb)
; #pragma unroll
;     for (int nt = 0; nt < 4; ++nt) Vf[kb][nt] = *(const bf16x8*)(c.Vbuf + ((kb * 4 + nt) * 64 + lane) * 8);
;   const float glc = g_;
; #pragma unroll
;   for (int nt = 0; nt < 4; ++nt) {
;     f32x4 o = {0.f, 0.f, 0.f, 0.f};
;     o = mfma16(QH_[0], Sf[0][nt], o); o = mfma16(QH_[1], Sf[1][nt], o);
;     o = mfma16(QK_[0], Vf[0][nt], o); o = mfma16(QK_[1], Vf[1][nt], o);
;     *(f32x4*)(c.Obuf + cb + ((w * 4 + nt) * 64 + lane) * 4) = o;
;     f32x4 sv = S[nt] * glc;
;     sv = mfma16(KT_[0], Vf[0][nt], sv); sv = mfma16(KT_[1], Vf[1][nt], sv);
;     S[nt] = sv;
;     *(uint2*)(Sn + (((w >> 1) * 4 + nt) * 64 + lane) * 8 + (w & 1) * 4) = pack4v(sv);
;   }
;   __builtin_amdgcn_sched_barrier(0);
;   scan_load(c, n + 2, W_, QH_, QK_, KT_, U_, g_);
	s_min_u32 s24, s13, 0x7d
	s_add_i32 s24, s24, s8
	s_ashr_i32 s25, s24, 31
	s_lshl_b64 s[26:27], s[24:25], 12
	v_lshl_add_u64 v[222:223], s[26:27], 0, v[112:113]
	v_lshlrev_b64 v[222:223], 1, v[222:223]
	v_lshl_add_u64 v[222:223], s[20:21], 0, v[222:223]
	s_lshl_b64 s[26:27], s[24:25], 14
	v_lshl_add_u64 v[224:225], v[116:117], 0, s[26:27]
	s_lshl_b64 s[28:29], s[24:25], 2
	s_add_u32 s28, s10, s28
	s_addc_u32 s29, s11, s29
	global_load_dwordx4 v[170:173], v[222:223], off
	global_load_dwordx4 v[174:177], v[222:223], off offset:1024
	global_load_dwordx4 v[178:181], v[224:225], off
	global_load_dwordx4 v[182:185], v[224:225], off offset:1024
	global_load_dwordx4 v[186:189], v[224:225], off offset:2048
	global_load_dwordx4 v[190:193], v[224:225], off offset:3072
	global_load_dword v194, v125, s[28:29]
	v_mfma_f32_16x16x32_bf16 v[48:51], v[16:19], v[150:153], v[48:51]
	ds_read_b128 v[52:55], v126 offset:16384
	ds_read_b128 v[64:67], v126 offset:17408
	ds_read_b128 v[68:71], v126 offset:20480
	ds_read_b128 v[72:75], v126 offset:21504
	s_waitcnt lgkmcnt(3)
	v_mfma_f32_16x16x32_bf16 v[48:51], v[0:3], v[52:55], v[48:51]
	v_mfma_f32_16x16x32_bf16 v[52:55], v[8:11], v[52:55], v[76:79]
	s_waitcnt lgkmcnt(1)
	v_mfma_f32_16x16x32_bf16 v[108:111], v[12:15], v[68:71], v[52:55]
	v_mfma_f32_16x16x32_bf16 v[52:55], v[4:7], v[134:137], 0
	v_mfma_f32_16x16x32_bf16 v[52:55], v[16:19], v[158:161], v[52:55]
	v_mfma_f32_16x16x32_bf16 v[48:51], v[20:23], v[68:71], v[48:51]
	v_mul_f32_e64 v70, v106, v118
	v_mul_f32_e64 v71, v107, v118
	v_pk_mul_f32 v[68:69], v[104:105], v[118:119] op_sel_hi:[1,0]
	v_mfma_f32_16x16x32_bf16 v[52:55], v[0:3], v[64:67], v[52:55]
	s_nop 0
	v_mfma_f32_16x16x32_bf16 v[64:67], v[8:11], v[64:67], v[68:71]
	s_waitcnt lgkmcnt(0)
	v_mfma_f32_16x16x32_bf16 v[104:107], v[12:15], v[72:75], v[64:67]
	v_mfma_f32_16x16x32_bf16 v[64:67], v[4:7], v[142:145], 0
	v_mfma_f32_16x16x32_bf16 v[4:7], v[4:7], v[146:149], 0
	v_mfma_f32_16x16x32_bf16 v[52:55], v[20:23], v[72:75], v[52:55]
	ds_read_b128 v[68:71], v126 offset:18432
	ds_read_b128 v[72:75], v126 offset:19456
	ds_read_b128 v[76:79], v126 offset:22528
	ds_read_b128 v[130:133], v126 offset:23552
	v_mfma_f32_16x16x32_bf16 v[64:67], v[16:19], v[162:165], v[64:67]
	v_mfma_f32_16x16x32_bf16 v[4:7], v[16:19], v[166:169], v[4:7]
	v_cvt_pk_bf16_f32 v16, v104, v105
	v_cvt_pk_bf16_f32 v17, v106, v107
	s_waitcnt lgkmcnt(3)
	v_mfma_f32_16x16x32_bf16 v[64:67], v[0:3], v[68:71], v[64:67]
	s_waitcnt lgkmcnt(2)
	v_mfma_f32_16x16x32_bf16 v[0:3], v[0:3], v[72:75], v[4:7]
	s_nop 2
	v_mul_f32_e64 v6, v98, v118
	v_mul_f32_e64 v7, v99, v118
	v_pk_mul_f32 v[4:5], v[96:97], v[118:119] op_sel_hi:[1,0]
	v_mfma_f32_16x16x32_bf16 v[68:71], v[8:11], v[68:71], v[100:103]
	s_nop 0
	v_mfma_f32_16x16x32_bf16 v[4:7], v[8:11], v[72:75], v[4:7]
	s_waitcnt lgkmcnt(1)
	v_mfma_f32_16x16x32_bf16 v[100:103], v[12:15], v[76:79], v[68:71]
	s_waitcnt lgkmcnt(0)
	v_mfma_f32_16x16x32_bf16 v[0:3], v[20:23], v[130:133], v[0:3]
	s_nop 1
	v_add_co_u32_e32 v68, vcc, s9, v120
	v_mfma_f32_16x16x32_bf16 v[96:99], v[12:15], v[130:133], v[4:7]
	s_nop 0
	v_addc_co_u32_e32 v69, vcc, -1, v121, vcc
	global_store_dwordx4 v[68:69], v[48:51], off offset:-3072
	v_mfma_f32_16x16x32_bf16 v[64:67], v[20:23], v[76:79], v[64:67]
	global_store_dwordx4 v[68:69], v[0:3], off
	v_cvt_pk_bf16_f32 v48, v108, v109
	v_cvt_pk_bf16_f32 v49, v110, v111
	ds_write2st64_b64 v127, v[48:49], v[16:17] offset0:16 offset1:18
	v_cvt_pk_bf16_f32 v16, v100, v101
	v_cvt_pk_bf16_f32 v17, v102, v103
	v_cvt_pk_bf16_f32 v0, v96, v97
	v_cvt_pk_bf16_f32 v1, v98, v99
	global_store_dwordx4 v[68:69], v[52:55], off offset:-2048
	global_store_dwordx4 v[68:69], v[64:67], off offset:-1024
	ds_write_b64 v128, v[16:17] offset:8192
	ds_write_b64 v129, v[0:1] offset:8192
	s_min_u32 s14, s13, 0x7d
	s_add_i32 s14, s14, s8
	s_ashr_i32 s15, s14, 31
	s_lshl_b64 s[16:17], s[14:15], 12
	v_lshl_add_u64 v[0:1], s[16:17], 0, v[112:113]
	v_lshlrev_b64 v[8:9], 1, v[0:1]
	v_lshl_add_u64 v[12:13], s[0:1], 0, v[8:9]
	v_lshl_add_u64 v[10:11], s[20:21], 0, v[8:9]
	v_lshl_add_u64 v[14:15], s[2:3], 0, v[8:9]
	global_load_dwordx4 v[4:7], v[12:13], off
	global_load_dwordx4 v[0:3], v[14:15], off
	v_lshl_add_u64 v[12:13], s[4:5], 0, v[8:9]
	v_lshl_add_u64 v[8:9], s[16:17], 0, v[114:115]
	v_lshlrev_b64 v[14:15], 1, v[8:9]
	v_lshl_add_u64 v[20:21], s[0:1], 0, v[14:15]
	v_lshl_add_u64 v[64:65], s[2:3], 0, v[14:15]
	s_lshl_b64 s[16:17], s[14:15], 14
	s_nop 0
	s_nop 0
	s_nop 0
	global_load_dwordx4 v[8:11], v[12:13], off
	global_load_dwordx4 v[16:19], v[20:21], off
	v_lshl_add_u64 v[66:67], s[4:5], 0, v[14:15]
	global_load_dwordx4 v[20:23], v[64:65], off
	global_load_dwordx4 v[12:15], v[66:67], off
	v_lshl_add_u64 v[64:65], v[116:117], 0, s[16:17]
	s_lshl_b64 s[14:15], s[14:15], 2
	s_nop 0
	s_nop 0
	s_nop 0
	s_nop 0
	s_nop 0
	s_add_u32 s14, s10, s14
	s_addc_u32 s15, s11, s15
	s_nop 0
	s_waitcnt lgkmcnt(0)
	s_barrier
	ds_read_b128 v[130:133], v126 offset:8192
	ds_read_b128 v[134:137], v126 offset:9216
	ds_read_b128 v[138:141], v126 offset:10240
	ds_read_b128 v[142:145], v126 offset:11264
	ds_read_b128 v[146:149], v126 offset:12288
	s_waitcnt vmcnt(27) lgkmcnt(4)


; __device__ __forceinline__ uint2 pack4v(f32x4 a) { uint2 r; r.x = pack2(a[0], a[1]); r.y = pack2(a[2], a[3]); return r; }
; __device__ __forceinline__ f32x4 mfma16(bf16x8 a, bf16x8 b, f32x4 c) { return __builtin_amdgcn_mfma_f32_16x16x32_bf16(a, b, c, 0, 0, 0); }
; __device__ __forceinline__ void scan_step(const ScanCtx& c, int n, const u16* Sc, u16* Sn, f32x4 (&S)[4], bf16x8 (&W_)[2], ...
;     ...
;   bf16x8 Sf[2][4];
; #pragma unroll
;   for (int kb = 0; kb < 2; ++kb)
; #pragma unroll
;     for (int nt = 0; nt < 4; ++nt) Sf[kb][nt] = *(const bf16x8*)(Sc + ((kb * 4 + nt) * 64 + lane) * 8);
; #pragma unroll
;   for (int nt = 0; nt < 4; ++nt) {
;     f32x4 a = {0.f, 0.f, 0.f, 0.f};
;     a = mfma16(W_[0], Sf[0][nt], a); a = mfma16(W_[1], Sf[1][nt], a);
;     f32x4 vn = U_[nt] - a;
;     *(uint2*)(c.Vbuf + (((w >> 1) * 4 + nt) * 64 + lane) * 8 + (w & 1) * 4) = pack4v(vn);
;   }
;   __syncthreads();
	v_mov_b32_e32 v122, v195
	v_mfma_f32_16x16x32_bf16 v[150:153], v[196:199], v[130:133], 0
	ds_read_b128 v[154:157], v126 offset:13312
	ds_read_b128 v[158:161], v126 offset:14336
	ds_read_b128 v[162:165], v126 offset:15360
	s_nop 0
	v_pk_mul_f32 v[102:103], v[122:123], v[102:103] op_sel_hi:[0,1]
	v_pk_mul_f32 v[100:101], v[122:123], v[100:101] op_sel_hi:[0,1]
	s_waitcnt lgkmcnt(3)
	v_mfma_f32_16x16x32_bf16 v[150:153], v[200:203], v[146:149], v[150:153]
	s_add_i32 s12, s12, 3
	v_mfma_f32_16x16x32_bf16 v[166:169], v[196:199], v[134:137], 0
	s_nop 0
	s_nop 4
	v_sub_f32_e32 v95, v207, v153
	v_sub_f32_e32 v94, v206, v152
	v_sub_f32_e32 v93, v205, v151
	v_sub_f32_e32 v92, v204, v150
	v_cvt_pk_bf16_f32 v150, v92, v93
	v_cvt_pk_bf16_f32 v151, v94, v95
	s_waitcnt lgkmcnt(2)
	v_mfma_f32_16x16x32_bf16 v[92:95], v[200:203], v[154:157], v[166:169]
	s_nop 0
	s_nop 6
	v_sub_f32_e32 v95, v211, v95
	v_sub_f32_e32 v94, v210, v94
	v_sub_f32_e32 v93, v209, v93
	v_sub_f32_e32 v92, v208, v92
	v_mfma_f32_16x16x32_bf16 v[88:91], v[196:199], v[138:141], 0
	v_cvt_pk_bf16_f32 v92, v92, v93
	v_cvt_pk_bf16_f32 v93, v94, v95
	ds_write2st64_b64 v127, v[150:151], v[92:93] offset0:32 offset1:34
	v_mfma_f32_16x16x32_bf16 v[60:63], v[196:199], v[142:145], 0
	v_mul_f32_e64 v94, v122, v110
	v_mul_f32_e64 v95, v122, v111
	v_pk_mul_f32 v[92:93], v[122:123], v[108:109] op_sel_hi:[0,1]
	s_waitcnt lgkmcnt(2)
	v_mfma_f32_16x16x32_bf16 v[88:91], v[200:203], v[158:161], v[88:91]
	s_waitcnt lgkmcnt(1)
	v_mfma_f32_16x16x32_bf16 v[56:59], v[200:203], v[162:165], v[60:63]
	s_nop 0
	s_nop 4
	v_sub_f32_e32 v87, v215, v91
	v_sub_f32_e32 v86, v214, v90
	v_sub_f32_e32 v85, v213, v89
	v_sub_f32_e32 v84, v212, v88
	s_nop 0
	v_sub_f32_e32 v59, v219, v59
	v_sub_f32_e32 v58, v218, v58
	v_sub_f32_e32 v57, v217, v57
	v_sub_f32_e32 v56, v216, v56
	v_cvt_pk_bf16_f32 v84, v84, v85
	v_cvt_pk_bf16_f32 v85, v86, v87
	v_cvt_pk_bf16_f32 v56, v56, v57
	v_cvt_pk_bf16_f32 v57, v58, v59
	ds_write_b64 v128, v[84:85] offset:16384
	ds_write_b64 v129, v[56:57] offset:16384
	s_waitcnt vmcnt(17)
	v_mfma_f32_16x16x32_bf16 v[56:59], v[28:31], v[130:133], 0
	s_waitcnt lgkmcnt(0)
	s_barrier
; __device__ __forceinline__ uint2 pack4v(f32x4 a) { uint2 r; r.x = pack2(a[0], a[1]); r.y = pack2(a[2], a[3]); return r; }
; __device__ __forceinline__ f32x4 mfma16(bf16x8 a, bf16x8 b, f32x4 c) { return __builtin_amdgcn_mfma_f32_16x16x32_bf16(a, b, c, 0, 0, 0); }
; __device__ __forceinline__ void scan_step(const ScanCtx& c, int n, const u16* Sc, u16* Sn, f32x4 (&S)[4], bf16x8 (&W_)[2], ...
;     ...
;   bf16x8 Vf[2][4];
; #pragma unroll
;   for (int kb = 0; kb < 2; ++kb)
; #pragma unroll
;     for (int nt = 0; nt < 4; ++nt) Vf[kb][nt] = *(const bf16x8*)(c.Vbuf + ((kb * 4 + nt) * 64 + lane) * 8);
;   const float glc = g_;
; #pragma unroll
;   for (int nt = 0; nt < 4; ++nt) {
;     f32x4 o = {0.f, 0.f, 0.f, 0.f};
;     o = mfma16(QH_[0], Sf[0][nt], o); o = mfma16(QH_[1], Sf[1][nt], o);
;     o = mfma16(QK_[0], Vf[0][nt], o); o = mfma16(QK_[1], Vf[1][nt], o);
;     *(f32x4*)(c.Obuf + cb + ((w * 4 + nt) * 64 + lane) * 4) = o;
;     f32x4 sv = S[nt] * glc;
;     sv = mfma16(KT_[0], Vf[0][nt], sv); sv = mfma16(KT_[1], Vf[1][nt], sv);
;     S[nt] = sv;
;     *(uint2*)(Sn + (((w >> 1) * 4 + nt) * 64 + lane) * 8 + (w & 1) * 4) = pack4v(sv);
;   }
;   __builtin_amdgcn_sched_barrier(0);
;   scan_load(c, n + 2, W_, QH_, QK_, KT_, U_, g_);
; __device__ void scan_seq(const P& p, int seq, u16* lds) {
;     ...
; #pragma unroll
;   for (int nt = 0; nt < 4; ++nt)
; #pragma unroll
;     for (int r = 0; r < 4; ++r) p.out[O_DP + ((size_t)seq * 64 + w * 16 + fq * 4 + r) * 64 + nt * 16 + fr] = S[nt][r];
	s_min_u32 s24, s12, 0x7d
	s_add_i32 s24, s24, s8
	s_ashr_i32 s25, s24, 31
	s_lshl_b64 s[26:27], s[24:25], 12
	v_lshl_add_u64 v[222:223], s[26:27], 0, v[112:113]
	v_lshlrev_b64 v[222:223], 1, v[222:223]
	v_lshl_add_u64 v[222:223], s[20:21], 0, v[222:223]
	s_lshl_b64 s[26:27], s[24:25], 14
	v_lshl_add_u64 v[224:225], v[116:117], 0, s[26:27]
	s_lshl_b64 s[28:29], s[24:25], 2
	s_add_u32 s28, s10, s28
	s_addc_u32 s29, s11, s29
	global_load_dwordx4 v[196:199], v[222:223], off
	global_load_dwordx4 v[200:203], v[222:223], off offset:1024
	global_load_dwordx4 v[204:207], v[224:225], off
	global_load_dwordx4 v[208:211], v[224:225], off offset:1024
	global_load_dwordx4 v[212:215], v[224:225], off offset:2048
	global_load_dwordx4 v[216:219], v[224:225], off offset:3072
	global_load_dword v195, v125, s[28:29]
	v_mfma_f32_16x16x32_bf16 v[56:59], v[40:43], v[146:149], v[56:59]
	ds_read_b128 v[60:63], v126 offset:16384
	ds_read_b128 v[80:83], v126 offset:17408
	ds_read_b128 v[84:87], v126 offset:20480
	ds_read_b128 v[88:91], v126 offset:21504
	s_waitcnt lgkmcnt(3)
	v_mfma_f32_16x16x32_bf16 v[56:59], v[24:27], v[60:63], v[56:59]
	v_mfma_f32_16x16x32_bf16 v[60:63], v[32:35], v[60:63], v[92:95]
	s_waitcnt lgkmcnt(1)
	v_mfma_f32_16x16x32_bf16 v[108:111], v[36:39], v[84:87], v[60:63]
	v_mfma_f32_16x16x32_bf16 v[60:63], v[28:31], v[134:137], 0
	v_mfma_f32_16x16x32_bf16 v[60:63], v[40:43], v[154:157], v[60:63]
	v_mfma_f32_16x16x32_bf16 v[56:59], v[44:47], v[84:87], v[56:59]
	v_mul_f32_e64 v86, v122, v106
	v_mul_f32_e64 v87, v122, v107
	v_pk_mul_f32 v[84:85], v[122:123], v[104:105] op_sel_hi:[0,1]
	v_mfma_f32_16x16x32_bf16 v[60:63], v[24:27], v[80:83], v[60:63]
	s_nop 0
	v_mfma_f32_16x16x32_bf16 v[80:83], v[32:35], v[80:83], v[84:87]
	s_waitcnt lgkmcnt(0)
	v_mfma_f32_16x16x32_bf16 v[104:107], v[36:39], v[88:91], v[80:83]
	v_mfma_f32_16x16x32_bf16 v[80:83], v[28:31], v[138:141], 0
	v_mfma_f32_16x16x32_bf16 v[28:31], v[28:31], v[142:145], 0
	v_mfma_f32_16x16x32_bf16 v[60:63], v[44:47], v[88:91], v[60:63]
	ds_read_b128 v[84:87], v126 offset:18432
	ds_read_b128 v[88:91], v126 offset:19456
	ds_read_b128 v[92:95], v126 offset:22528
	ds_read_b128 v[130:133], v126 offset:23552
	global_store_dwordx4 v[120:121], v[56:59], off offset:-3072
	v_mfma_f32_16x16x32_bf16 v[80:83], v[40:43], v[158:161], v[80:83]
	s_nop 1
	global_store_dwordx4 v[120:121], v[60:63], off offset:-2048
	v_cvt_pk_bf16_f32 v56, v108, v109
	v_cvt_pk_bf16_f32 v57, v110, v111
	v_mfma_f32_16x16x32_bf16 v[28:31], v[40:43], v[162:165], v[28:31]
	v_cvt_pk_bf16_f32 v40, v104, v105
	v_cvt_pk_bf16_f32 v41, v106, v107
	ds_write2st64_b64 v127, v[56:57], v[40:41] offset1:2
	s_waitcnt lgkmcnt(4)
	v_mfma_f32_16x16x32_bf16 v[80:83], v[24:27], v[84:87], v[80:83]
	s_waitcnt lgkmcnt(3)
	v_mfma_f32_16x16x32_bf16 v[24:27], v[24:27], v[88:91], v[28:31]
	s_nop 2
	v_mul_f32_e64 v30, v122, v98
	v_mul_f32_e64 v31, v122, v99
	v_pk_mul_f32 v[28:29], v[122:123], v[96:97] op_sel_hi:[0,1]
	v_mfma_f32_16x16x32_bf16 v[84:87], v[32:35], v[84:87], v[100:103]
	s_nop 0
	v_mfma_f32_16x16x32_bf16 v[28:31], v[32:35], v[88:91], v[28:31]
	s_waitcnt lgkmcnt(2)
	v_mfma_f32_16x16x32_bf16 v[100:103], v[36:39], v[92:95], v[84:87]
	s_waitcnt lgkmcnt(1)
	v_mfma_f32_16x16x32_bf16 v[24:27], v[44:47], v[130:133], v[24:27]
	v_mfma_f32_16x16x32_bf16 v[96:99], v[36:39], v[130:133], v[28:31]
	s_nop 4
	v_cvt_pk_bf16_f32 v40, v100, v101
	v_cvt_pk_bf16_f32 v41, v102, v103
	global_store_dwordx4 v[120:121], v[24:27], off
	v_mfma_f32_16x16x32_bf16 v[80:83], v[44:47], v[92:95], v[80:83]
	ds_write_b64 v128, v[40:41]
	v_cvt_pk_bf16_f32 v24, v96, v97
	v_cvt_pk_bf16_f32 v25, v98, v99
	ds_write_b64 v129, v[24:25]
	s_nop 3
	global_store_dwordx4 v[120:121], v[80:83], off offset:-1024
	s_min_u32 s12, s12, 0x7d
	s_add_i32 s14, s12, s8
	s_ashr_i32 s15, s14, 31
	s_lshl_b64 s[16:17], s[14:15], 12
	v_lshl_add_u64 v[24:25], s[16:17], 0, v[112:113]
	v_lshlrev_b64 v[32:33], 1, v[24:25]
	v_lshl_add_u64 v[34:35], s[20:21], 0, v[32:33]
	v_lshl_add_u64 v[24:25], s[0:1], 0, v[32:33]
	v_lshl_add_u64 v[26:27], s[2:3], 0, v[32:33]
	v_lshl_add_u64 v[36:37], s[4:5], 0, v[32:33]
	v_lshl_add_u64 v[32:33], s[16:17], 0, v[114:115]
	v_lshlrev_b64 v[38:39], 1, v[32:33]
	v_lshl_add_u64 v[44:45], s[0:1], 0, v[38:39]
	v_lshl_add_u64 v[80:81], s[2:3], 0, v[38:39]
	s_lshl_b64 s[16:17], s[14:15], 14
	global_load_dwordx4 v[28:31], v[24:25], off
	s_nop 0
	global_load_dwordx4 v[24:27], v[26:27], off
	s_nop 0
	s_nop 0
	s_nop 0
	s_nop 0
	global_load_dwordx4 v[32:35], v[36:37], off
	global_load_dwordx4 v[40:43], v[44:45], off
	v_lshl_add_u64 v[82:83], s[4:5], 0, v[38:39]
	global_load_dwordx4 v[44:47], v[80:81], off
	global_load_dwordx4 v[36:39], v[82:83], off
	v_lshl_add_u64 v[80:81], v[116:117], 0, s[16:17]
	s_lshl_b64 s[14:15], s[14:15], 2
	s_nop 0
	s_nop 0
	s_nop 0
	s_nop 0
	s_nop 0
	s_add_u32 s14, s10, s14
	s_addc_u32 s15, s11, s15
	s_nop 0
	v_lshl_add_u64 v[120:121], v[120:121], 0, s[6:7]
	s_cmpk_lt_u32 s13, 0x7e
	s_mov_b32 s12, s13
	s_waitcnt lgkmcnt(0)
	s_barrier
	s_cbranch_scc1 .LBB0_483
	v_readlane_b32 s0, v228, 0
	v_readlane_b32 s1, v228, 1
	s_mov_b32 s2, s0
	s_ashr_i32 s3, s0, 31
	v_writelane_b32 v228, s0, 0
	s_waitcnt vmcnt(0)
	v_lshlrev_b32_e32 v0, 4, v124
	v_ashrrev_i32_e32 v1, 31, v0
	v_writelane_b32 v228, s1, 1
	s_lshl_b64 s[0:1], s[2:3], 6
	v_lshl_add_u64 v[0:1], s[0:1], 0, v[0:1]
	v_lshrrev_b32_e32 v3, 2, v123
	v_and_or_b32 v0, v3, 12, v0
	v_and_b32_e32 v2, 15, v123
	v_lshlrev_b64 v[0:1], 8, v[0:1]
	v_lshl_add_u64 v[0:1], s[20:21], 0, v[0:1]
	v_lshlrev_b32_e32 v2, 2, v2
	v_mov_b32_e32 v3, 0
	v_lshl_add_u64 v[0:1], v[0:1], 0, v[2:3]
	s_mov_b32 s0, 0x8492000
	v_add_co_u32_e32 v0, vcc, s0, v0
	s_nop 1
	v_addc_co_u32_e32 v1, vcc, 0, v1, vcc
	global_store_dword v[0:1], v108, off
	global_store_dword v[0:1], v109, off offset:256
	global_store_dword v[0:1], v110, off offset:512
	global_store_dword v[0:1], v111, off offset:768
	global_store_dword v[0:1], v104, off offset:64
	global_store_dword v[0:1], v105, off offset:320
	global_store_dword v[0:1], v106, off offset:576
	global_store_dword v[0:1], v107, off offset:832
	global_store_dword v[0:1], v100, off offset:128
	global_store_dword v[0:1], v101, off offset:384
	global_store_dword v[0:1], v102, off offset:640
	global_store_dword v[0:1], v103, off offset:896
	global_store_dword v[0:1], v96, off offset:192
	global_store_dword v[0:1], v97, off offset:448
	global_store_dword v[0:1], v98, off offset:704
	global_store_dword v[0:1], v99, off offset:960
